# v52 with the attention fast loop shifted by 4 bytes (code placement phase), later code positions unchanged
# speedup vs baseline: 1.0022x; 1.0022x over previous
.LBB0_1318:
	s_sub_i32 s33, s33, 64
	s_sub_i32 s93, s93, 64
	s_add_u32 s90, s90, 0xffffffc0
	s_addc_u32 s91, s91, -1
	s_add_u32 s72, s72, 0x20000
	s_addc_u32 s73, s73, 0
	s_add_i32 s4, s95, 1
	s_cmp_eq_u32 s95, s70
	v_add_u32_e32 v179, 64, v179
	s_cbranch_scc1 .LBB0_1320
	s_mov_b32 s8, s78
	s_mov_b32 s78, s88
	s_mov_b32 s88, s71
	s_mov_b32 s95, s4
	s_branch .LBB0_1304
	s_nop 0
.Latt_flA_top:
	s_lshl_b32 s6, s8, 14
	v_add_u32_e32 v228, s6, v163
	v_add_u32_e32 v229, s6, v164
	v_add_u32_e32 v230, s6, v165
	v_add_u32_e32 v231, s6, v166
	ds_read_b128 v[96:99], v228
	ds_read_b128 v[200:203], v229
	ds_read_b128 v[204:207], v230
	ds_read_b128 v[208:211], v231
	ds_read_b128 v[112:115], v228 offset:8192
	ds_read_b128 v[216:219], v229 offset:8192
	ds_read_b128 v[220:223], v230 offset:8192
	ds_read_b128 v[224:227], v231 offset:8192
	s_add_u32 s98, s0, s72
	s_addc_u32 s99, s1, s73
	s_lshl_b32 s4, s88, 14
	s_add_i32 s5, s87, s4
	s_mov_b32 m0, s5
	s_add_i32 s4, s95, 2
	s_and_b32 s4, s4, 3
	s_lshl_b32 s4, s4, 14
	s_add_i32 s4, s85, s4
	s_waitcnt lgkmcnt(7)
	v_mfma_f32_32x32x16_bf16 v[96:111], v[96:99], v[132:135], 0
	s_waitcnt lgkmcnt(6)
	v_mfma_f32_32x32x16_bf16 v[96:111], v[200:203], v[136:139], v[96:111]
	s_waitcnt lgkmcnt(5)
	v_mfma_f32_32x32x16_bf16 v[96:111], v[204:207], v[140:143], v[96:111]
	s_waitcnt lgkmcnt(4)
	v_mfma_f32_32x32x16_bf16 v[96:111], v[208:211], v[144:147], v[96:111]
	s_waitcnt lgkmcnt(3)
	v_mfma_f32_32x32x16_bf16 v[112:127], v[112:115], v[132:135], 0
	global_load_lds_dwordx4 v239, s[98:99]
	s_addk_i32 s5, 0x400
	s_mov_b32 m0, s5
	s_waitcnt lgkmcnt(2)
	v_mfma_f32_32x32x16_bf16 v[112:127], v[216:219], v[136:139], v[112:127]
	global_load_lds_dwordx4 v240, s[98:99]
	s_add_u32 s98, s66, s72
	s_addc_u32 s99, s67, s73
	s_mov_b32 m0, s4
	s_addk_i32 s4, 0x400
	s_waitcnt lgkmcnt(1)
	v_mfma_f32_32x32x16_bf16 v[112:127], v[220:223], v[140:143], v[112:127]
	global_load_lds_dwordx4 v241, s[98:99]
	s_mov_b32 m0, s4
	s_waitcnt lgkmcnt(0)
	v_mfma_f32_32x32x16_bf16 v[112:127], v[224:227], v[144:147], v[112:127]
	global_load_lds_dwordx4 v242, s[98:99]
	s_and_b32 s7, s95, 3
	s_lshl_b32 s7, s7, 14
	v_add_u32_e32 v243, s7, v7
	v_add_u32_e32 v244, s7, v9
	v_add_u32_e32 v245, s7, v10
	v_add_u32_e32 v246, s7, v11
	ds_read_b64_tr_b16 v[188:189], v243 offset:49152
	ds_read_b64_tr_b16 v[190:191], v243 offset:51200
	ds_read_b64_tr_b16 v[192:193], v244
	ds_read_b64_tr_b16 v[194:195], v244 offset:2048
	ds_read_b64_tr_b16 v[196:197], v245
	ds_read_b64_tr_b16 v[198:199], v245 offset:2048
	ds_read_b64_tr_b16 v[200:201], v246
	ds_read_b64_tr_b16 v[202:203], v246 offset:2048
	v_exp_f32_e32 v228, v96
	v_exp_f32_e32 v229, v97
	v_exp_f32_e32 v230, v98
	v_exp_f32_e32 v231, v99
	v_exp_f32_e32 v232, v100
	v_exp_f32_e32 v233, v101
	v_exp_f32_e32 v234, v102
	v_exp_f32_e32 v187, v103
	v_cvt_pk_bf16_f32 v220, v228, v229
	v_cvt_pk_bf16_f32 v221, v230, v231
	v_cvt_pk_bf16_f32 v222, v232, v233
	v_cvt_pk_bf16_f32 v223, v234, v187
	ds_read_b64_tr_b16 v[204:205], v243 offset:53248
	ds_read_b64_tr_b16 v[206:207], v243 offset:55296
	ds_read_b64_tr_b16 v[208:209], v244 offset:4096
	ds_read_b64_tr_b16 v[210:211], v244 offset:6144
	ds_read_b64_tr_b16 v[212:213], v245 offset:4096
	ds_read_b64_tr_b16 v[214:215], v245 offset:6144
	ds_read_b64_tr_b16 v[216:217], v246 offset:4096
	ds_read_b64_tr_b16 v[218:219], v246 offset:6144
	s_waitcnt lgkmcnt(8)
	v_mfma_f32_32x32x16_bf16 v[80:95], v[188:191], v[220:223], v[80:95]
	ds_read_b64_tr_b16 v[188:189], v243 offset:57344
	ds_read_b64_tr_b16 v[190:191], v243 offset:59392
	v_exp_f32_e32 v247, v104
	v_exp_f32_e32 v248, v105
	v_add_f32_e32 v153, 0, v228
	v_add_f32_e32 v153, v229, v153
	v_mfma_f32_32x32x16_bf16 v[64:79], v[192:195], v[220:223], v[64:79]
	ds_read_b64_tr_b16 v[192:193], v244 offset:8192
	ds_read_b64_tr_b16 v[194:195], v244 offset:10240
	v_exp_f32_e32 v249, v106
	v_exp_f32_e32 v250, v107
	v_add_f32_e32 v153, v230, v153
	v_add_f32_e32 v153, v231, v153
	v_mfma_f32_32x32x16_bf16 v[48:63], v[196:199], v[220:223], v[48:63]
	ds_read_b64_tr_b16 v[196:197], v245 offset:8192
	ds_read_b64_tr_b16 v[198:199], v245 offset:10240
	v_exp_f32_e32 v251, v108
	v_exp_f32_e32 v252, v109
	v_add_f32_e32 v153, v232, v153
	v_add_f32_e32 v153, v233, v153
	v_mfma_f32_32x32x16_bf16 v[32:47], v[200:203], v[220:223], v[32:47]
	ds_read_b64_tr_b16 v[200:201], v246 offset:8192
	ds_read_b64_tr_b16 v[202:203], v246 offset:10240
	v_exp_f32_e32 v253, v110
	v_exp_f32_e32 v254, v111
	v_cvt_pk_bf16_f32 v224, v247, v248
	v_cvt_pk_bf16_f32 v225, v249, v250
	v_cvt_pk_bf16_f32 v226, v251, v252
	v_cvt_pk_bf16_f32 v227, v253, v254
	v_add_f32_e32 v153, v234, v153
	v_add_f32_e32 v153, v187, v153
	s_waitcnt lgkmcnt(8)
	v_mfma_f32_32x32x16_bf16 v[80:95], v[204:207], v[224:227], v[80:95]
	ds_read_b64_tr_b16 v[204:205], v243 offset:61440
	ds_read_b64_tr_b16 v[206:207], v243 offset:63488
	v_exp_f32_e32 v228, v112
	v_exp_f32_e32 v229, v113
	v_add_f32_e32 v153, v247, v153
	v_add_f32_e32 v153, v248, v153
	v_mfma_f32_32x32x16_bf16 v[64:79], v[208:211], v[224:227], v[64:79]
	ds_read_b64_tr_b16 v[208:209], v244 offset:12288
	ds_read_b64_tr_b16 v[210:211], v244 offset:14336
	v_exp_f32_e32 v230, v114
	v_exp_f32_e32 v231, v115
	v_add_f32_e32 v153, v249, v153
	v_add_f32_e32 v153, v250, v153
	v_mfma_f32_32x32x16_bf16 v[48:63], v[212:215], v[224:227], v[48:63]
	ds_read_b64_tr_b16 v[212:213], v245 offset:12288
	ds_read_b64_tr_b16 v[214:215], v245 offset:14336
	v_exp_f32_e32 v232, v116
	v_exp_f32_e32 v233, v117
	v_add_f32_e32 v153, v251, v153
	v_add_f32_e32 v153, v252, v153
	v_mfma_f32_32x32x16_bf16 v[32:47], v[216:219], v[224:227], v[32:47]
	ds_read_b64_tr_b16 v[216:217], v246 offset:12288
	ds_read_b64_tr_b16 v[218:219], v246 offset:14336
	v_exp_f32_e32 v234, v118
	v_exp_f32_e32 v187, v119
	v_cvt_pk_bf16_f32 v220, v228, v229
	v_cvt_pk_bf16_f32 v221, v230, v231
	v_cvt_pk_bf16_f32 v222, v232, v233
	v_cvt_pk_bf16_f32 v223, v234, v187
	v_add_f32_e32 v153, v253, v153
	v_add_f32_e32 v153, v254, v153
	s_waitcnt lgkmcnt(8)
	v_mfma_f32_32x32x16_bf16 v[80:95], v[188:191], v[220:223], v[80:95]
	v_exp_f32_e32 v247, v120
	v_exp_f32_e32 v248, v121
	v_add_f32_e32 v153, v228, v153
	v_add_f32_e32 v153, v229, v153
	v_mfma_f32_32x32x16_bf16 v[64:79], v[192:195], v[220:223], v[64:79]
	v_exp_f32_e32 v249, v122
	v_exp_f32_e32 v250, v123
	v_add_f32_e32 v153, v230, v153
	v_add_f32_e32 v153, v231, v153
	v_mfma_f32_32x32x16_bf16 v[48:63], v[196:199], v[220:223], v[48:63]
	v_exp_f32_e32 v251, v124
	v_exp_f32_e32 v252, v125
	v_add_f32_e32 v153, v232, v153
	v_add_f32_e32 v153, v233, v153
	v_mfma_f32_32x32x16_bf16 v[32:47], v[200:203], v[220:223], v[32:47]
	v_exp_f32_e32 v253, v126
	v_exp_f32_e32 v254, v127
	v_cvt_pk_bf16_f32 v224, v247, v248
	v_cvt_pk_bf16_f32 v225, v249, v250
	v_cvt_pk_bf16_f32 v226, v251, v252
	v_cvt_pk_bf16_f32 v227, v253, v254
	v_add_f32_e32 v153, v234, v153
	v_add_f32_e32 v153, v187, v153
	s_waitcnt lgkmcnt(0)
	v_mfma_f32_32x32x16_bf16 v[80:95], v[204:207], v[224:227], v[80:95]
	v_add_f32_e32 v153, v247, v153
	v_add_f32_e32 v153, v248, v153
	v_mfma_f32_32x32x16_bf16 v[64:79], v[208:211], v[224:227], v[64:79]
	v_add_f32_e32 v153, v249, v153
	v_add_f32_e32 v153, v250, v153
	v_mfma_f32_32x32x16_bf16 v[48:63], v[212:215], v[224:227], v[48:63]
	v_add_f32_e32 v153, v251, v153
	v_add_f32_e32 v153, v252, v153
	v_mfma_f32_32x32x16_bf16 v[32:47], v[216:219], v[224:227], v[32:47]
	v_add_f32_e32 v153, v253, v153
	v_add_f32_e32 v153, v254, v153
	v_add_f32_e32 v6, v6, v153
	s_add_u32 s72, s72, 0x20000
	s_addc_u32 s73, s73, 0
	s_add_i32 s95, s95, 1
	s_mov_b32 s71, s8
	s_mov_b32 s8, s78
	s_mov_b32 s78, s88
	s_mov_b32 s88, s71
	s_sub_i32 s101, s101, 1
	s_cmp_lg_u32 s101, 0
	s_waitcnt vmcnt(4) lgkmcnt(0)
	s_barrier
	s_cbranch_scc1 .Latt_flA_top
	s_nop 0
	s_lshl_b32 s4, s100, 6
	s_sub_i32 s33, s33, s4
	s_sub_i32 s93, s93, s4
	s_sub_u32 s90, s90, s4
	s_subb_u32 s91, s91, 0
	v_add_u32_e32 v179, s4, v179
	s_branch .Latt_slow
